# nt hint also on the 48 16-byte loads of the one-time prologue (f32 inputs x and weights are read exactly once)
# speedup vs baseline: 1.0327x; 1.0161x over previous
; #define LAS __attribute__((address_space(3)))
; DI void tr_item(const float* W, int ldw, const float* gain, bf16_t* WT, int ldk, int k0, int n0, bool remap, LAS float* scr, int lane) {
;     const int nq = (lane & 7) * 4, kr = lane >> 3; const int nn = n0 + nq; const int src = remap ? map_in(nn) : nn;
;     f32x4 v[8];
; #pragma unroll
;     for (int i = 0; i < 8; ++i) { const int kk = 8 * i + kr;
;         v[i] = (f32x4){0.f, 0.f, 0.f, 0.f}; if (src >= 0) { v[i] = *(const f32x4*)(W + (size_t)(k0 + kk) * ldw + src); if (gain) v[i] = v[i] * gain[k0 + kk]; } }
; DI void p0_prologue(const Params& p, LAS unsigned char* lds, int tid, int lane, int wave) {
;     ...
;         tr_item(p.w_ukv + (size_t)l * 128 * 1024, 1024, p.kv_norm_g + l * 128, (bf16_t*)(ws + WS_WUP) + ((size_t)l * WUP_ROWS + 768) * 256, 256, 64 * (r / 32), 32 * (r % 32), false, scr, lane);
.LBB0_11:
	s_mul_hi_i32 s4, s70, 0x4325c53f
	s_lshr_b32 s5, s4, 31
	s_ashr_i32 s4, s4, 9
	s_add_i32 s18, s4, s5
	s_mul_i32 s4, s18, 0xfffff860
	s_add_i32 s6, s70, s4
	s_ashr_i32 s19, s18, 31
	s_cmpk_gt_i32 s6, 0x4ff
	s_mov_b64 s[4:5], -1
	s_cbranch_scc0 .LBB0_52
	s_cmpk_gt_u32 s6, 0x6ff
	s_cbranch_scc0 .LBB0_49
	s_cmpk_gt_u32 s6, 0x75f
	s_mul_hi_i32 s7, s18, 0xe0000
	s_mul_i32 s22, s18, 0xe0000
	s_cbranch_scc0 .LBB0_31
	s_lshl_b64 s[4:5], s[18:19], 19
	s_add_u32 s4, s40, s4
	s_addc_u32 s5, s41, s5
	s_lshl_b32 s24, s18, 7
	s_ashr_i32 s25, s24, 31
	s_lshl_b64 s[24:25], s[24:25], 2
	s_add_u32 s26, s38, s24
	s_mul_i32 s23, s18, 0xfffff0c0
	s_addc_u32 s27, s39, s25
	s_add_i32 s23, s55, s23
	s_addk_i32 s23, 0xfb40
	s_and_b32 s24, s23, 0x7fffffc0
	s_and_b32 s23, s53, 0x3e0
	v_or_b32_e32 v2, s23, v35
	v_add_u32_e32 v6, s24, v37
	v_lshlrev_b32_e32 v38, 2, v2
	v_ashrrev_i32_e32 v7, 31, v6
	v_lshl_add_u64 v[2:3], s[4:5], 0, v[38:39]
	v_lshlrev_b64 v[4:5], 12, v[6:7]
	v_lshl_add_u64 v[30:31], v[2:3], 0, v[4:5]
	global_load_dwordx4 v[2:5], v[30:31], off nt
	v_cmp_ne_u32_e64 s[4:5], 1, v50
	s_andn2_b64 vcc, exec, s[12:13]
	v_lshl_add_u64 v[40:41], v[6:7], 2, s[26:27]
	s_cbranch_vccnz .LBB0_16
	global_load_dword v6, v[40:41], off
	s_waitcnt vmcnt(0)
	v_pk_mul_f32 v[4:5], v[4:5], v[6:7] op_sel_hi:[1,0]
	v_pk_mul_f32 v[2:3], v[2:3], v[6:7] op_sel_hi:[1,0]
.LBB0_16:
	v_add_co_u32_e32 v6, vcc, 0x8000, v30
	s_nop 1
	v_addc_co_u32_e32 v7, vcc, 0, v31, vcc
	global_load_dwordx4 v[6:9], v[6:7], off nt
	s_and_b64 vcc, exec, s[4:5]
	s_cbranch_vccnz .LBB0_18
	global_load_dword v10, v[40:41], off offset:32
	s_waitcnt vmcnt(0)
	v_pk_mul_f32 v[8:9], v[8:9], v[10:11] op_sel_hi:[1,0]
	v_pk_mul_f32 v[6:7], v[6:7], v[10:11] op_sel_hi:[1,0]
.LBB0_18:
	v_add_co_u32_e32 v10, vcc, 0x10000, v30
	s_nop 1
	v_addc_co_u32_e32 v11, vcc, 0, v31, vcc
	global_load_dwordx4 v[10:13], v[10:11], off nt
	s_and_b64 vcc, exec, s[4:5]
	s_cbranch_vccnz .LBB0_20
	global_load_dword v14, v[40:41], off offset:64
	s_waitcnt vmcnt(0)
	v_pk_mul_f32 v[12:13], v[12:13], v[14:15] op_sel_hi:[1,0]
	v_pk_mul_f32 v[10:11], v[10:11], v[14:15] op_sel_hi:[1,0]
.LBB0_20:
	v_add_co_u32_e32 v14, vcc, 0x18000, v30
	s_nop 1
	v_addc_co_u32_e32 v15, vcc, 0, v31, vcc
	global_load_dwordx4 v[14:17], v[14:15], off nt
	s_and_b64 vcc, exec, s[4:5]
	s_cbranch_vccnz .LBB0_22
	global_load_dword v18, v[40:41], off offset:96
	s_waitcnt vmcnt(0)
	v_pk_mul_f32 v[16:17], v[16:17], v[18:19] op_sel_hi:[1,0]
	v_pk_mul_f32 v[14:15], v[14:15], v[18:19] op_sel_hi:[1,0]
.LBB0_22:
	v_add_co_u32_e32 v18, vcc, 0x20000, v30
	s_nop 1
	v_addc_co_u32_e32 v19, vcc, 0, v31, vcc
	global_load_dwordx4 v[18:21], v[18:19], off nt
	s_and_b64 vcc, exec, s[4:5]
	s_cbranch_vccnz .LBB0_24
	global_load_dword v22, v[40:41], off offset:128
	s_waitcnt vmcnt(0)
	v_pk_mul_f32 v[20:21], v[20:21], v[22:23] op_sel_hi:[1,0]
	v_pk_mul_f32 v[18:19], v[18:19], v[22:23] op_sel_hi:[1,0]
.LBB0_24:
	v_add_co_u32_e32 v22, vcc, 0x28000, v30
	s_nop 1
	v_addc_co_u32_e32 v23, vcc, 0, v31, vcc
	global_load_dwordx4 v[22:25], v[22:23], off nt
	s_and_b64 vcc, exec, s[4:5]
	s_cbranch_vccnz .LBB0_26
	global_load_dword v26, v[40:41], off offset:160
	s_waitcnt vmcnt(0)
	v_pk_mul_f32 v[24:25], v[24:25], v[26:27] op_sel_hi:[1,0]
	v_pk_mul_f32 v[22:23], v[22:23], v[26:27] op_sel_hi:[1,0]
.LBB0_26:
	v_add_co_u32_e32 v26, vcc, 0x30000, v30
	s_nop 1
	v_addc_co_u32_e32 v27, vcc, 0, v31, vcc
	global_load_dwordx4 v[26:29], v[26:27], off nt
	s_and_b64 vcc, exec, s[4:5]
	s_cbranch_vccnz .LBB0_28
	global_load_dword v32, v[40:41], off offset:192
	s_waitcnt vmcnt(0)
	v_pk_mul_f32 v[28:29], v[28:29], v[32:33] op_sel_hi:[1,0]
	v_pk_mul_f32 v[26:27], v[26:27], v[32:33] op_sel_hi:[1,0]
.LBB0_28:
	v_add_co_u32_e32 v30, vcc, 0x38000, v30
	s_nop 1
	v_addc_co_u32_e32 v31, vcc, 0, v31, vcc
	global_load_dwordx4 v[30:33], v[30:31], off nt
	s_and_b64 vcc, exec, s[4:5]
	s_cbranch_vccnz .LBB0_30
	global_load_dword v38, v[40:41], off offset:224
	s_waitcnt vmcnt(0)
	v_pk_mul_f32 v[32:33], v[32:33], v[38:39] op_sel_hi:[1,0]
	v_pk_mul_f32 v[30:31], v[30:31], v[38:39] op_sel_hi:[1,0]

; #define LAS __attribute__((address_space(3)))
; DI void tr_item(const float* W, int ldw, const float* gain, bf16_t* WT, int ldk, int k0, int n0, bool remap, LAS float* scr, int lane) {
;     const int nq = (lane & 7) * 4, kr = lane >> 3; const int nn = n0 + nq; const int src = remap ? map_in(nn) : nn;
;     f32x4 v[8];
; #pragma unroll
;     for (int i = 0; i < 8; ++i) { const int kk = 8 * i + kr;
;         v[i] = (f32x4){0.f, 0.f, 0.f, 0.f}; if (src >= 0) { v[i] = *(const f32x4*)(W + (size_t)(k0 + kk) * ldw + src); if (gain) v[i] = v[i] * gain[k0 + kk]; } }
; DI void p0_prologue(const Params& p, LAS unsigned char* lds, int tid, int lane, int wave) {
;     ...
;         if (r < IT_UQ) { tr_item(p.w_uq + (size_t)l * 256 * 768, 768, p.q_norm_g + l * 256, (bf16_t*)(ws + WS_WUP) + (size_t)l * WUP_ROWS * 256, 256, 64 * (r / 24), 32 * (r % 24), false, scr, lane); continue; } r -= IT_UQ;
.LBB0_31:
	s_and_b64 vcc, exec, s[4:5]
	s_cbranch_vccz .LBB0_87
	s_mul_i32 s4, s18, 0xc0000
	s_mul_hi_i32 s5, s18, 0xc0000
	s_add_u32 s4, s36, s4
	s_addc_u32 s5, s37, s5
	s_lshl_b32 s24, s18, 8
	s_ashr_i32 s25, s24, 31
	v_readlane_b32 s72, v254, 2
	s_lshl_b64 s[24:25], s[24:25], 2
	v_readlane_b32 s86, v254, 16
	v_readlane_b32 s87, v254, 17
	s_add_u32 s26, s86, s24
	s_addc_u32 s27, s87, s25
	s_and_b32 s23, s6, 0xff
	s_mulk_i32 s23, 0xab
	s_lshr_b32 s23, s23, 12
	s_lshl_b32 s24, s23, 6
	s_mul_i32 s23, s23, 24
	s_sub_i32 s23, s6, s23
	s_and_b32 s23, s23, 0xff
	s_lshl_b32 s23, s23, 5
	v_or_b32_e32 v2, s23, v35
	v_lshlrev_b32_e32 v38, 2, v2
	v_add_u32_e32 v30, s24, v37
	v_lshl_add_u64 v[32:33], s[4:5], 0, v[38:39]
	v_mad_i64_i32 v[2:3], s[4:5], v30, s64, v[32:33]
	global_load_dwordx4 v[2:5], v[2:3], off nt
	v_ashrrev_i32_e32 v31, 31, v30
	v_cndmask_b32_e64 v6, 0, 1, s[14:15]
	v_cmp_ne_u32_e64 s[4:5], 1, v6
	s_andn2_b64 vcc, exec, s[14:15]
	v_lshl_add_u64 v[40:41], v[30:31], 2, s[26:27]
	v_readlane_b32 s73, v254, 3
	v_readlane_b32 s74, v254, 4
	v_readlane_b32 s75, v254, 5
	v_readlane_b32 s76, v254, 6
	v_readlane_b32 s77, v254, 7
	v_readlane_b32 s78, v254, 8
	v_readlane_b32 s79, v254, 9
	v_readlane_b32 s80, v254, 10
	v_readlane_b32 s81, v254, 11
	v_readlane_b32 s82, v254, 12
	v_readlane_b32 s83, v254, 13
	v_readlane_b32 s84, v254, 14
	v_readlane_b32 s85, v254, 15
	s_cbranch_vccnz .LBB0_34
	global_load_dword v6, v[40:41], off
	s_waitcnt vmcnt(0)
	v_pk_mul_f32 v[4:5], v[4:5], v[6:7] op_sel_hi:[1,0]
	v_pk_mul_f32 v[2:3], v[2:3], v[6:7] op_sel_hi:[1,0]
.LBB0_34:
	v_add_u32_e32 v6, 8, v30
	v_mad_i64_i32 v[6:7], s[26:27], v6, s64, v[32:33]
	global_load_dwordx4 v[6:9], v[6:7], off nt
	s_and_b64 vcc, exec, s[4:5]
	s_cbranch_vccnz .LBB0_36
	global_load_dword v10, v[40:41], off offset:32
	s_waitcnt vmcnt(0)
	v_pk_mul_f32 v[8:9], v[8:9], v[10:11] op_sel_hi:[1,0]
	v_pk_mul_f32 v[6:7], v[6:7], v[10:11] op_sel_hi:[1,0]
.LBB0_36:
	v_add_u32_e32 v10, 16, v30
	v_mad_i64_i32 v[10:11], s[26:27], v10, s64, v[32:33]
	global_load_dwordx4 v[10:13], v[10:11], off nt
	s_and_b64 vcc, exec, s[4:5]
	s_cbranch_vccnz .LBB0_38
	global_load_dword v14, v[40:41], off offset:64
	s_waitcnt vmcnt(0)
	v_pk_mul_f32 v[12:13], v[12:13], v[14:15] op_sel_hi:[1,0]
	v_pk_mul_f32 v[10:11], v[10:11], v[14:15] op_sel_hi:[1,0]
.LBB0_38:
	v_add_u32_e32 v14, 24, v30
	v_mad_i64_i32 v[14:15], s[26:27], v14, s64, v[32:33]
	global_load_dwordx4 v[14:17], v[14:15], off nt
	s_and_b64 vcc, exec, s[4:5]
	s_cbranch_vccnz .LBB0_40
	global_load_dword v18, v[40:41], off offset:96
	s_waitcnt vmcnt(0)
	v_pk_mul_f32 v[16:17], v[16:17], v[18:19] op_sel_hi:[1,0]
	v_pk_mul_f32 v[14:15], v[14:15], v[18:19] op_sel_hi:[1,0]
.LBB0_40:
	v_add_u32_e32 v18, 32, v30
	v_mad_i64_i32 v[18:19], s[26:27], v18, s64, v[32:33]
	global_load_dwordx4 v[18:21], v[18:19], off nt
	s_and_b64 vcc, exec, s[4:5]
	s_cbranch_vccnz .LBB0_42
	global_load_dword v22, v[40:41], off offset:128
	s_waitcnt vmcnt(0)
	v_pk_mul_f32 v[20:21], v[20:21], v[22:23] op_sel_hi:[1,0]
	v_pk_mul_f32 v[18:19], v[18:19], v[22:23] op_sel_hi:[1,0]
.LBB0_42:
	v_add_u32_e32 v22, 40, v30
	v_mad_i64_i32 v[22:23], s[26:27], v22, s64, v[32:33]
	global_load_dwordx4 v[22:25], v[22:23], off nt
	s_and_b64 vcc, exec, s[4:5]
	s_cbranch_vccnz .LBB0_44
	global_load_dword v26, v[40:41], off offset:160
	s_waitcnt vmcnt(0)
	v_pk_mul_f32 v[24:25], v[24:25], v[26:27] op_sel_hi:[1,0]
	v_pk_mul_f32 v[22:23], v[22:23], v[26:27] op_sel_hi:[1,0]
.LBB0_44:
	v_add_u32_e32 v26, 48, v30
	v_mad_i64_i32 v[26:27], s[26:27], v26, s64, v[32:33]
	global_load_dwordx4 v[26:29], v[26:27], off nt
	s_and_b64 vcc, exec, s[4:5]
	s_cbranch_vccnz .LBB0_46
	global_load_dword v38, v[40:41], off offset:192
	s_waitcnt vmcnt(0)
	v_pk_mul_f32 v[28:29], v[28:29], v[38:39] op_sel_hi:[1,0]
	v_pk_mul_f32 v[26:27], v[26:27], v[38:39] op_sel_hi:[1,0]
.LBB0_46:
	v_add_u32_e32 v30, 56, v30
	v_mad_i64_i32 v[30:31], s[26:27], v30, s64, v[32:33]
	global_load_dwordx4 v[30:33], v[30:31], off nt
	s_and_b64 vcc, exec, s[4:5]
	s_cbranch_vccnz .LBB0_48
	global_load_dword v38, v[40:41], off offset:224
	s_waitcnt vmcnt(0)
	v_pk_mul_f32 v[32:33], v[32:33], v[38:39] op_sel_hi:[1,0]
	v_pk_mul_f32 v[30:31], v[30:31], v[38:39] op_sel_hi:[1,0]

; #define LAS __attribute__((address_space(3)))
; DI unsigned pk2(float lo, float hi) { f32x2 v = {lo, hi}; return __builtin_bit_cast(unsigned, __builtin_convertvector(v, bf2_t)); }
; DI void tr_item(const float* W, int ldw, const float* gain, bf16_t* WT, int ldk, int k0, int n0, bool remap, LAS float* scr, int lane) {
;     const int nq = (lane & 7) * 4, kr = lane >> 3; const int nn = n0 + nq; const int src = remap ? map_in(nn) : nn;
;     f32x4 v[8];
; #pragma unroll
;     for (int i = 0; i < 8; ++i) { const int kk = 8 * i + kr;
;         v[i] = (f32x4){0.f, 0.f, 0.f, 0.f}; if (src >= 0) { v[i] = *(const f32x4*)(W + (size_t)(k0 + kk) * ldw + src); if (gain) v[i] = v[i] * gain[k0 + kk]; } }
; #pragma unroll
;     for (int i = 0; i < 8; ++i) *(LAS f32x4*)(scr + (8 * i + kr) * 36 + nq) = v[i];
;     asm volatile("s_waitcnt lgkmcnt(0)" ::: "memory");
;     const int c = lane & 7;
; #pragma unroll
;     for (int j = 0; j < 4; ++j) { const int n = (lane >> 3) + 8 * j; const LAS float* s = scr + (8 * c) * 36 + n;
;         u32x4 o; o.x = pk2(s[0 * 36], s[1 * 36]); o.y = pk2(s[2 * 36], s[3 * 36]); o.z = pk2(s[4 * 36], s[5 * 36]); o.w = pk2(s[6 * 36], s[7 * 36]);
;         *(u32x4*)(WT + (size_t)(n0 + n) * ldk + k0 + 8 * c) = o; }
;     asm volatile("s_waitcnt lgkmcnt(0)" ::: "memory");
; DI void p0_prologue(const Params& p, LAS unsigned char* lds, int tid, int lane, int wave) {
;     ...
;         if (r < IT_OUT) { tr_item(p.w_out + (size_t)l * DM * DM, DM, nullptr, (bf16_t*)(ws + WS_WOUT) + (size_t)l * DM * DM, DM, 64 * (r / 32), 32 * (r % 32), false, scr, lane); continue; } r -= IT_OUT;
.LBB0_50:
	s_lshl_b64 s[4:5], s[18:19], 22
	s_add_u32 s22, s46, s4
	s_addc_u32 s23, s47, s5
	s_lshl_b64 s[4:5], s[18:19], 21
	s_add_u32 s7, s31, s4
	s_mul_i32 s4, s18, 0xfffff0c0
	s_addc_u32 s5, s34, s5
	s_add_i32 s4, s55, s4
	s_and_b32 s19, s4, 0x7fffffc0
	s_and_b32 s4, s53, 0x3e0
	v_or_b32_e32 v3, s4, v35
	v_add_u32_e32 v2, s19, v37
	v_lshlrev_b32_e32 v38, 2, v3
	v_ashrrev_i32_e32 v3, 31, v2
	v_lshl_add_u64 v[4:5], s[22:23], 0, v[38:39]
	v_lshlrev_b64 v[2:3], 12, v[2:3]
	v_lshl_add_u64 v[26:27], v[4:5], 0, v[2:3]
	v_add_co_u32_e32 v6, vcc, s57, v26
	v_add_u32_e32 v51, v44, v45
	s_nop 0
	v_addc_co_u32_e32 v7, vcc, 0, v27, vcc
	v_add_co_u32_e32 v10, vcc, s58, v26
	global_load_dwordx4 v[2:5], v[26:27], off nt
	s_nop 0
	global_load_dwordx4 v[6:9], v[6:7], off nt
	v_addc_co_u32_e32 v11, vcc, 0, v27, vcc
	v_add_co_u32_e32 v14, vcc, s59, v26
	s_lshl_b32 s19, s19, 1
	s_nop 0
	v_addc_co_u32_e32 v15, vcc, 0, v27, vcc
	v_add_co_u32_e32 v18, vcc, s60, v26
	global_load_dwordx4 v[10:13], v[10:11], off nt
	s_nop 0
	global_load_dwordx4 v[14:17], v[14:15], off nt
	v_addc_co_u32_e32 v19, vcc, 0, v27, vcc
	v_add_co_u32_e32 v22, vcc, s61, v26
	v_add_u32_e32 v40, s4, v37
	s_nop 0
	v_addc_co_u32_e32 v23, vcc, 0, v27, vcc
	v_add_co_u32_e32 v28, vcc, s62, v26
	global_load_dwordx4 v[18:21], v[18:19], off nt
	s_nop 0
	global_load_dwordx4 v[22:25], v[22:23], off nt
	v_addc_co_u32_e32 v29, vcc, 0, v27, vcc
	v_add_co_u32_e32 v30, vcc, s63, v26
	s_add_u32 s22, s7, s19
	s_nop 0
	v_addc_co_u32_e32 v31, vcc, 0, v27, vcc
	global_load_dwordx4 v[26:29], v[28:29], off nt
	s_nop 0
	global_load_dwordx4 v[30:33], v[30:31], off nt
	v_ashrrev_i32_e32 v41, 31, v40
	v_lshlrev_b32_e32 v38, 1, v36
	s_addc_u32 s23, s5, 0
	v_lshlrev_b64 v[40:41], 11, v[40:41]
	v_lshl_add_u64 v[52:53], s[22:23], 0, v[38:39]
	v_add_u32_e32 v42, s4, v46
	v_ashrrev_i32_e32 v43, 31, v42
	v_lshlrev_b64 v[42:43], 11, v[42:43]
	s_waitcnt vmcnt(0)
	ds_write_b128 v51, v[2:5]
	ds_write_b128 v51, v[6:9] offset:1152
	ds_write_b128 v51, v[10:13] offset:2304
	ds_write_b128 v51, v[14:17] offset:3456
	ds_write_b128 v51, v[18:21] offset:4608
	ds_write_b128 v51, v[22:25] offset:5760
	ds_write_b128 v51, v[26:29] offset:6912
	ds_write_b128 v51, v[30:33] offset:8064
	s_waitcnt lgkmcnt(0)
	ds_read_b32 v2, v49
	ds_read_b32 v3, v49 offset:144
	ds_read_b32 v4, v49 offset:288
	ds_read_b32 v5, v49 offset:432
	ds_read_b32 v8, v49 offset:576
	ds_read_b32 v9, v49 offset:720
	ds_read_b32 v10, v49 offset:864
	ds_read_b32 v11, v49 offset:1008
	v_lshl_add_u64 v[6:7], v[52:53], 0, v[40:41]
	s_waitcnt lgkmcnt(0)
	v_cvt_pk_bf16_f32 v2, v2, v3
	v_cvt_pk_bf16_f32 v3, v4, v5
	v_cvt_pk_bf16_f32 v4, v8, v9
	v_cvt_pk_bf16_f32 v5, v10, v11
	flat_store_dwordx4 v[6:7], v[2:5]
	ds_read_b32 v2, v49 offset:32
	ds_read_b32 v3, v49 offset:176
	ds_read_b32 v4, v49 offset:320
	ds_read_b32 v5, v49 offset:464
	ds_read_b32 v8, v49 offset:608
	ds_read_b32 v9, v49 offset:752
	ds_read_b32 v10, v49 offset:896
	ds_read_b32 v11, v49 offset:1040
	v_lshl_add_u64 v[6:7], v[52:53], 0, v[42:43]
	s_waitcnt lgkmcnt(0)
	v_cvt_pk_bf16_f32 v2, v2, v3
	v_cvt_pk_bf16_f32 v3, v4, v5
	v_cvt_pk_bf16_f32 v4, v8, v9
	v_cvt_pk_bf16_f32 v5, v10, v11
	flat_store_dwordx4 v[6:7], v[2:5]
	ds_read_b32 v2, v49 offset:64
	ds_read_b32 v3, v49 offset:208
	ds_read_b32 v4, v49 offset:352
	ds_read_b32 v5, v49 offset:496
	ds_read_b32 v6, v49 offset:640
	ds_read_b32 v7, v49 offset:784
	ds_read_b32 v8, v49 offset:928
	ds_read_b32 v9, v49 offset:1072
	s_waitcnt lgkmcnt(0)
	v_cvt_pk_bf16_f32 v2, v2, v3
	v_cvt_pk_bf16_f32 v3, v4, v5
	v_cvt_pk_bf16_f32 v4, v6, v7
	v_add_u32_e32 v6, s4, v47
	v_ashrrev_i32_e32 v7, 31, v6
	v_lshlrev_b64 v[6:7], 11, v[6:7]
	v_cvt_pk_bf16_f32 v5, v8, v9
	v_lshl_add_u64 v[6:7], v[52:53], 0, v[6:7]
	flat_store_dwordx4 v[6:7], v[2:5]
	ds_read_b32 v2, v49 offset:96
	ds_read_b32 v3, v49 offset:240
	ds_read_b32 v4, v49 offset:384
	ds_read_b32 v5, v49 offset:528
	ds_read_b32 v6, v49 offset:672
	ds_read_b32 v7, v49 offset:816
	ds_read_b32 v8, v49 offset:960
	ds_read_b32 v9, v49 offset:1104
	s_waitcnt lgkmcnt(0)
	v_cvt_pk_bf16_f32 v2, v2, v3
	v_cvt_pk_bf16_f32 v3, v4, v5
	v_cvt_pk_bf16_f32 v4, v6, v7
	v_add_u32_e32 v6, s4, v48
	v_ashrrev_i32_e32 v7, 31, v6
	v_lshlrev_b64 v[6:7], 11, v[6:7]
	v_cvt_pk_bf16_f32 v5, v8, v9
	v_lshl_add_u64 v[6:7], v[52:53], 0, v[6:7]
	flat_store_dwordx4 v[6:7], v[2:5]
	s_waitcnt lgkmcnt(0)

; #define LAS __attribute__((address_space(3)))
; DI void tr_item(const float* W, int ldw, const float* gain, bf16_t* WT, int ldk, int k0, int n0, bool remap, LAS float* scr, int lane) {
;     const int nq = (lane & 7) * 4, kr = lane >> 3; const int nn = n0 + nq; const int src = remap ? map_in(nn) : nn;
;     f32x4 v[8];
; #pragma unroll
;     for (int i = 0; i < 8; ++i) { const int kk = 8 * i + kr;
;         v[i] = (f32x4){0.f, 0.f, 0.f, 0.f}; if (src >= 0) { v[i] = *(const f32x4*)(W + (size_t)(k0 + kk) * ldw + src); if (gain) v[i] = v[i] * gain[k0 + kk]; } }
; DI void p0_prologue(const Params& p, LAS unsigned char* lds, int tid, int lane, int wave) {
;     ...
;         if (r < IT_IN) { tr_item(p.w_in + (size_t)l * DM * DIN, DIN, p.norm_g + l * DM, (bf16_t*)(ws + WS_WIN) + (size_t)l * N1 * DM, DM, 64 * (r / 80), 32 * (r % 80), true, scr, lane); continue; } r -= IT_IN;
.LBB0_63:
	s_or_b64 exec, exec, s[4:5]
	v_readlane_b32 s72, v254, 2
	s_mul_i32 s4, s18, 0x9d0000
	v_readlane_b32 s78, v254, 8
	s_mul_hi_i32 s5, s18, 0x9d0000
	v_readlane_b32 s79, v254, 9
	s_add_u32 s4, s78, s4
	s_addc_u32 s5, s79, s5
	s_lshl_b32 s6, s18, 10
	s_ashr_i32 s7, s6, 31
	v_readlane_b32 s76, v254, 6
	s_lshl_b64 s[6:7], s[6:7], 2
	v_readlane_b32 s77, v254, 7
	s_add_u32 s24, s76, s6
	s_sext_i32_i16 s6, s22
	s_addc_u32 s25, s77, s7
	s_lshl_b32 s22, s6, 6
	v_cndmask_b32_e64 v3, 0, 1, s[16:17]
	v_cmp_lt_i32_e64 s[6:7], -1, v38
	v_add_u32_e32 v40, s22, v37
	v_lshl_add_u64 v[42:43], v[38:39], 2, s[4:5]
	v_mov_b32_e32 v2, 0
	v_cmp_ne_u32_e64 s[4:5], 1, v3
	v_mov_b32_e32 v6, 0
	v_mov_b32_e32 v7, 0
	v_mov_b32_e32 v8, 0
	v_mov_b32_e32 v9, 0
	v_readlane_b32 s73, v254, 3
	v_readlane_b32 s74, v254, 4
	v_readlane_b32 s75, v254, 5
	v_readlane_b32 s80, v254, 10
	v_readlane_b32 s81, v254, 11
	v_readlane_b32 s82, v254, 12
	v_readlane_b32 s83, v254, 13
	v_readlane_b32 s84, v254, 14
	v_readlane_b32 s85, v254, 15
	v_readlane_b32 s86, v254, 16
	v_readlane_b32 s87, v254, 17
	s_and_saveexec_b64 s[26:27], s[6:7]
	s_cbranch_execz .LBB0_66
	v_mad_i64_i32 v[4:5], s[72:73], v40, s67, v[42:43]
	global_load_dwordx4 v[6:9], v[4:5], off nt
	s_and_b64 vcc, exec, s[4:5]
	s_cbranch_vccnz .LBB0_66
	v_ashrrev_i32_e32 v41, 31, v40
	v_lshl_add_u64 v[4:5], v[40:41], 2, s[24:25]
	global_load_dword v4, v[4:5], off
	s_waitcnt vmcnt(0)
	v_pk_mul_f32 v[8:9], v[8:9], v[4:5] op_sel_hi:[1,0]
	v_pk_mul_f32 v[6:7], v[6:7], v[4:5] op_sel_hi:[1,0]
.LBB0_66:
	s_or_b64 exec, exec, s[26:27]
	v_mov_b32_e32 v3, 0
	v_mov_b32_e32 v4, 0
	v_mov_b32_e32 v5, 0
	s_and_saveexec_b64 s[26:27], s[6:7]
	s_cbranch_execz .LBB0_69
	v_add_u32_e32 v2, 8, v40
	v_mad_i64_i32 v[2:3], s[72:73], v2, s67, v[42:43]
	global_load_dwordx4 v[2:5], v[2:3], off nt
	s_and_b64 vcc, exec, s[4:5]
	s_cbranch_vccnz .LBB0_69
	v_ashrrev_i32_e32 v41, 31, v40
	v_lshl_add_u64 v[10:11], v[40:41], 2, s[24:25]
	global_load_dword v10, v[10:11], off offset:32
	s_waitcnt vmcnt(0)
	v_pk_mul_f32 v[4:5], v[4:5], v[10:11] op_sel_hi:[1,0]
	v_pk_mul_f32 v[2:3], v[2:3], v[10:11] op_sel_hi:[1,0]
.LBB0_69:
	s_or_b64 exec, exec, s[26:27]
	v_mov_b32_e32 v10, 0
	v_mov_b32_e32 v14, 0
	v_mov_b32_e32 v15, 0
	v_mov_b32_e32 v16, 0
	v_mov_b32_e32 v17, 0
	s_and_saveexec_b64 s[26:27], s[6:7]
	s_cbranch_execz .LBB0_72
	v_add_u32_e32 v11, 16, v40
	v_mad_i64_i32 v[12:13], s[72:73], v11, s67, v[42:43]
	global_load_dwordx4 v[14:17], v[12:13], off nt
	s_and_b64 vcc, exec, s[4:5]
	s_cbranch_vccnz .LBB0_72
	v_ashrrev_i32_e32 v41, 31, v40
	v_lshl_add_u64 v[12:13], v[40:41], 2, s[24:25]
	global_load_dword v12, v[12:13], off offset:64
	s_waitcnt vmcnt(0)
	v_pk_mul_f32 v[16:17], v[16:17], v[12:13] op_sel_hi:[1,0]
	v_pk_mul_f32 v[14:15], v[14:15], v[12:13] op_sel_hi:[1,0]
.LBB0_72:
	s_or_b64 exec, exec, s[26:27]
	v_mov_b32_e32 v11, 0
	v_mov_b32_e32 v12, 0
	v_mov_b32_e32 v13, 0
	s_and_saveexec_b64 s[26:27], s[6:7]
	s_cbranch_execz .LBB0_75
	v_add_u32_e32 v10, 24, v40
	v_mad_i64_i32 v[10:11], s[72:73], v10, s67, v[42:43]
	global_load_dwordx4 v[10:13], v[10:11], off nt
	s_and_b64 vcc, exec, s[4:5]
	s_cbranch_vccnz .LBB0_75
	v_ashrrev_i32_e32 v41, 31, v40
	v_lshl_add_u64 v[18:19], v[40:41], 2, s[24:25]
	global_load_dword v18, v[18:19], off offset:96
	s_waitcnt vmcnt(0)
	v_pk_mul_f32 v[12:13], v[12:13], v[18:19] op_sel_hi:[1,0]
	v_pk_mul_f32 v[10:11], v[10:11], v[18:19] op_sel_hi:[1,0]
.LBB0_75:
	s_or_b64 exec, exec, s[26:27]
	v_mov_b32_e32 v18, 0
	v_mov_b32_e32 v22, 0
	v_mov_b32_e32 v23, 0
	v_mov_b32_e32 v24, 0
	v_mov_b32_e32 v25, 0
	s_and_saveexec_b64 s[26:27], s[6:7]
	s_cbranch_execz .LBB0_78
	v_add_u32_e32 v19, 32, v40
	v_mad_i64_i32 v[20:21], s[72:73], v19, s67, v[42:43]
	global_load_dwordx4 v[22:25], v[20:21], off nt
	s_and_b64 vcc, exec, s[4:5]
	s_cbranch_vccnz .LBB0_78
	v_ashrrev_i32_e32 v41, 31, v40
	v_lshl_add_u64 v[20:21], v[40:41], 2, s[24:25]
	global_load_dword v20, v[20:21], off offset:128
	s_waitcnt vmcnt(0)
	v_pk_mul_f32 v[24:25], v[24:25], v[20:21] op_sel_hi:[1,0]
	v_pk_mul_f32 v[22:23], v[22:23], v[20:21] op_sel_hi:[1,0]
.LBB0_78:
	s_or_b64 exec, exec, s[26:27]
	v_mov_b32_e32 v19, 0
	v_mov_b32_e32 v20, 0
	v_mov_b32_e32 v21, 0
	s_and_saveexec_b64 s[26:27], s[6:7]
	s_cbranch_execz .LBB0_81
	v_add_u32_e32 v18, 40, v40
	v_mad_i64_i32 v[18:19], s[72:73], v18, s67, v[42:43]
	global_load_dwordx4 v[18:21], v[18:19], off nt
	s_and_b64 vcc, exec, s[4:5]
	s_cbranch_vccnz .LBB0_81
	v_ashrrev_i32_e32 v41, 31, v40
	v_lshl_add_u64 v[26:27], v[40:41], 2, s[24:25]
	global_load_dword v26, v[26:27], off offset:160
	s_waitcnt vmcnt(0)
	v_pk_mul_f32 v[20:21], v[20:21], v[26:27] op_sel_hi:[1,0]
	v_pk_mul_f32 v[18:19], v[18:19], v[26:27] op_sel_hi:[1,0]
.LBB0_81:
	s_or_b64 exec, exec, s[26:27]
	v_mov_b32_e32 v26, 0
	v_mov_b32_e32 v30, 0
	v_mov_b32_e32 v31, 0
	v_mov_b32_e32 v32, 0
	v_mov_b32_e32 v33, 0
	s_and_saveexec_b64 s[26:27], s[6:7]
	s_cbranch_execz .LBB0_84
	v_add_u32_e32 v27, 48, v40
	v_mad_i64_i32 v[28:29], s[72:73], v27, s67, v[42:43]
	global_load_dwordx4 v[30:33], v[28:29], off nt
	s_and_b64 vcc, exec, s[4:5]
	s_cbranch_vccnz .LBB0_84
	v_ashrrev_i32_e32 v41, 31, v40
	v_lshl_add_u64 v[28:29], v[40:41], 2, s[24:25]
	global_load_dword v28, v[28:29], off offset:192
	s_waitcnt vmcnt(0)
	v_pk_mul_f32 v[32:33], v[32:33], v[28:29] op_sel_hi:[1,0]
	v_pk_mul_f32 v[30:31], v[30:31], v[28:29] op_sel_hi:[1,0]
.LBB0_84:
	s_or_b64 exec, exec, s[26:27]
	v_mov_b32_e32 v27, 0
	v_mov_b32_e32 v28, 0
	v_mov_b32_e32 v29, 0
	s_and_saveexec_b64 s[26:27], s[6:7]
	s_cbranch_execz .LBB0_9
	v_add_u32_e32 v26, 56, v40
	v_mad_i64_i32 v[26:27], s[6:7], v26, s67, v[42:43]
	global_load_dwordx4 v[26:29], v[26:27], off nt
	s_and_b64 vcc, exec, s[4:5]
	s_cbranch_vccnz .LBB0_9
	v_ashrrev_i32_e32 v41, 31, v40
	v_lshl_add_u64 v[40:41], v[40:41], 2, s[24:25]
	global_load_dword v38, v[40:41], off offset:224
	s_waitcnt vmcnt(0)
	v_pk_mul_f32 v[28:29], v[28:29], v[38:39] op_sel_hi:[1,0]
	v_pk_mul_f32 v[26:27], v[26:27], v[38:39] op_sel_hi:[1,0]
	s_branch .LBB0_9

; DI unsigned pk2(float lo, float hi) { f32x2 v = {lo, hi}; return __builtin_bit_cast(unsigned, __builtin_convertvector(v, bf2_t)); }
; DI void p0_prologue(const Params& p, LAS unsigned char* lds, int tid, int lane, int wave) {
;     ...
;     for (int m0 = gw * 4; m0 < T; m0 += NGW * 4) {
;         f32x4 v[4][4];
; #pragma unroll
;         for (int q = 0; q < 4; ++q)
; #pragma unroll
;             for (int j = 0; j < 4; ++j) v[q][j] = ((const f32x4*)(p.x + (size_t)(m0 + q) * DM) + lane)[64 * j];
; #pragma unroll
;         for (int q = 0; q < 4; ++q) {
;             float s = 0.f;
;             unsigned long long* o8 = (unsigned long long*)(XB + (size_t)(m0 + q) * DM) + lane;
; #pragma unroll
;             for (int j = 0; j < 4; ++j) { const f32x4 w = v[q][j]; s += (w.x * w.x + w.y * w.y) + (w.z * w.z + w.w * w.w);
;                 o8[64 * j] = (unsigned long long)pk2(w.x, w.y) | ((unsigned long long)pk2(w.z, w.w) << 32); }
;             s = wave_sum(s, lane); if (lane < 16) SSQ[(size_t)(m0 + q) * 16 + lane] = (lane == 0) ? s : 0.f;
;         }
.LBB0_115:
	v_add_co_u32_e32 v18, vcc, 0xffffd000, v54
	v_lshl_add_u64 v[58:59], s[0:1], 0, v[52:53]
	s_nop 0
	v_addc_co_u32_e32 v19, vcc, -1, v55, vcc
	global_load_dwordx4 v[62:65], v[18:19], off offset:-3072 nt
	global_load_dwordx4 v[66:69], v[18:19], off offset:-2048 nt
	global_load_dwordx4 v[70:73], v[18:19], off offset:-1024 nt
	global_load_dwordx4 v[74:77], v[18:19], off nt
	global_load_dwordx4 v[6:9], v[54:55], off offset:-3072 nt
	global_load_dwordx4 v[2:5], v[54:55], off offset:-2048 nt
	global_load_dwordx4 v[14:17], v[54:55], off offset:-1024 nt
	global_load_dwordx4 v[10:13], v[54:55], off nt
	v_add_co_u32_e32 v18, vcc, 0xffffe000, v54
	s_waitcnt vmcnt(0)
	v_mul_f32_e32 v84, v63, v63
	v_addc_co_u32_e32 v19, vcc, -1, v55, vcc
	v_add_co_u32_e32 v56, vcc, 0xfffff000, v54
	global_load_dwordx4 v[46:49], v[18:19], off offset:-3072 nt
	global_load_dwordx4 v[42:45], v[18:19], off offset:-2048 nt
	global_load_dwordx4 v[38:41], v[18:19], off offset:-1024 nt
	global_load_dwordx4 v[34:37], v[18:19], off nt
	v_addc_co_u32_e32 v57, vcc, -1, v55, vcc
	global_load_dwordx4 v[30:33], v[56:57], off offset:-3072 nt
	global_load_dwordx4 v[26:29], v[56:57], off offset:-2048 nt
	global_load_dwordx4 v[22:25], v[56:57], off offset:-1024 nt
	global_load_dwordx4 v[18:21], v[54:55], off offset:-4096 nt
	v_add_co_u32_e32 v60, vcc, s3, v58
	v_mul_f32_e32 v85, v65, v65
	v_cvt_pk_bf16_f32 v56, v62, v63
	v_cvt_pk_bf16_f32 v57, v64, v65
	v_mul_f32_e32 v63, v67, v67
	v_mul_f32_e32 v65, v69, v69
	v_addc_co_u32_e32 v61, vcc, 0, v59, vcc
	v_cvt_pk_bf16_f32 v78, v66, v67
	v_cvt_pk_bf16_f32 v79, v68, v69
	v_mul_f32_e32 v67, v71, v71
	v_mul_f32_e32 v69, v73, v73
	v_fmac_f32_e32 v84, v62, v62
	v_fmac_f32_e32 v85, v64, v64
	v_fmac_f32_e32 v63, v66, v66
	v_fmac_f32_e32 v65, v68, v68
	v_cvt_pk_bf16_f32 v80, v70, v71
	v_cvt_pk_bf16_f32 v81, v72, v73
	v_mul_f32_e32 v71, v75, v75
	v_mul_f32_e32 v73, v77, v77
	v_cvt_pk_bf16_f32 v82, v74, v75
	v_cvt_pk_bf16_f32 v83, v76, v77
	v_fmac_f32_e32 v67, v70, v70
	v_fmac_f32_e32 v69, v72, v72
	flat_store_dwordx2 v[60:61], v[56:57]
	flat_store_dwordx2 v[60:61], v[78:79] offset:512
	flat_store_dwordx2 v[60:61], v[80:81] offset:1024
	flat_store_dwordx2 v[60:61], v[82:83] offset:1536
	v_add_f32_e32 v56, v84, v85
	v_add_f32_e32 v57, v63, v65
	v_fmac_f32_e32 v71, v74, v74
	v_fmac_f32_e32 v73, v76, v76
	v_add_f32_e32 v62, v67, v69
	v_add_f32_e32 v56, v56, v57
	v_add_f32_e32 v63, v71, v73
	v_add_f32_e32 v56, v56, v62
	v_add_f32_e32 v56, v56, v63
	s_nop 1
	v_add_f32_dpp v56, v56, v56 row_ror:1 row_mask:0xf bank_mask:0xf bound_ctrl:1
	s_nop 1
	v_add_f32_dpp v56, v56, v56 row_ror:2 row_mask:0xf bank_mask:0xf bound_ctrl:1
	s_nop 1
	v_add_f32_dpp v56, v56, v56 row_ror:4 row_mask:0xf bank_mask:0xf bound_ctrl:1
	s_nop 1
	v_add_f32_dpp v56, v56, v56 row_ror:8 row_mask:0xf bank_mask:0xf bound_ctrl:1
	s_nop 0
	v_readlane_b32 s26, v56, 0
	v_readlane_b32 s15, v56, 16
	v_readlane_b32 s27, v56, 32
	v_readlane_b32 s20, v56, 48
	v_lshl_add_u64 v[56:57], s[0:1], 0, v[50:51]
	s_and_saveexec_b64 s[24:25], s[4:5]
	s_cbranch_execz .LBB0_117
	v_mov_b32_e32 v62, s15
	v_mov_b32_e32 v63, s20
	v_pk_add_f32 v[62:63], s[26:27], v[62:63]
	s_nop 0
	v_add_f32_e32 v62, v62, v63
	v_cndmask_b32_e64 v64, 0, v62, s[6:7]
	v_add_co_u32_e32 v62, vcc, 0x2500000, v56
	s_nop 1
	v_addc_co_u32_e32 v63, vcc, 0, v57, vcc
	flat_store_dword v[62:63], v64
